# RG-LRU loops: 14+14 always-true conv-tap selects and their scalar compare chains removed; dead next-item register copies (35+19 per item) removed
# speedup vs baseline: 1.0055x; 1.0055x over previous
.LBB0_92:
	s_add_i32 s36, s36, 1
	s_cmp_ge_i32 s36, s37
	s_cselect_b64 s[4:5], -1, 0
	s_and_b64 vcc, exec, s[4:5]
	v_lshlrev_b32_e32 v128, 1, v132
	s_waitcnt vmcnt(0)
	s_cbranch_vccnz .LBB0_94
	s_ashr_i32 s0, s36, 5
	s_mul_hi_i32 s1, s0, 0x2aaaaaab
	s_lshr_b32 s25, s1, 31
	s_ashr_i32 s1, s1, 1
	s_add_i32 s1, s1, s25
	s_mul_i32 s25, s1, -12
	s_add_i32 s25, s25, s0
	s_lshl_b32 s0, s36, 7
	s_and_b32 s0, s0, 0xf80
	s_add_i32 s26, s0, s77
	s_mul_hi_i32 s0, s1, 0x1e00000
	s_mul_i32 s1, s1, 0x1e00000
	s_add_u32 s27, s33, s1
	s_addc_u32 s38, s68, s0
	s_lshl_b32 s0, s25, 6
	s_ashr_i32 s1, s0, 31
	s_lshl_b64 s[0:1], s[0:1], 1
	s_add_u32 s0, s27, s0
	s_addc_u32 s1, s38, s1
	v_lshl_add_u64 v[68:69], s[0:1], 0, v[128:129]
	s_mov_b64 s[0:1], 0x1200
	v_lshl_add_u64 v[68:69], v[68:69], 0, s[0:1]
	s_max_i32 s0, s26, 3
	s_add_i32 s0, s0, -3
	v_mad_u64_u32 v[142:143], s[0:1], s0, v165, v[68:69]
	s_max_i32 s0, s26, 2
	s_add_i32 s0, s0, -2
	global_load_ushort v141, v[142:143], off
	v_mad_u64_u32 v[142:143], s[0:1], s0, v165, v[68:69]
	s_max_i32 s0, s26, 1
	s_add_i32 s0, s0, -1
	v_mad_u64_u32 v[144:145], s[0:1], s0, v165, v[68:69]
	s_max_i32 s0, s26, 0
	global_load_ushort v142, v[142:143], off
	s_or_b32 s25, s26, 1
	global_load_ushort v143, v[144:145], off
	v_mad_u64_u32 v[144:145], s[0:1], s0, v165, v[68:69]
	s_max_i32 s0, s25, 0
	s_nop 0
	v_mad_u64_u32 v[146:147], s[0:1], s0, v165, v[68:69]
	s_or_b32 s27, s26, 2
	s_max_i32 s0, s27, 0
	global_load_ushort v144, v[144:145], off
	s_or_b32 s38, s26, 3
	global_load_ushort v145, v[146:147], off
	v_mad_u64_u32 v[146:147], s[0:1], s0, v165, v[68:69]
	s_max_i32 s0, s38, 0
	s_nop 0
	v_mad_u64_u32 v[148:149], s[0:1], s0, v165, v[68:69]
	s_or_b32 s39, s26, 4
	s_max_i32 s0, s39, 0
	global_load_ushort v146, v[146:147], off
	s_or_b32 s40, s26, 5
	global_load_ushort v147, v[148:149], off
	v_mad_u64_u32 v[148:149], s[0:1], s0, v165, v[68:69]
	s_max_i32 s0, s40, 0
	s_nop 0
	v_mad_u64_u32 v[150:151], s[0:1], s0, v165, v[68:69]
	s_or_b32 s41, s26, 6
	s_max_i32 s0, s41, 0
	global_load_ushort v148, v[148:149], off
	s_or_b32 s42, s26, 7
	global_load_ushort v149, v[150:151], off
	v_mad_u64_u32 v[150:151], s[0:1], s0, v165, v[68:69]
	s_max_i32 s0, s42, 0
	s_nop 0
	v_mad_u64_u32 v[152:153], s[0:1], s0, v165, v[68:69]
	s_or_b32 s43, s26, 8
	s_max_i32 s0, s43, 0
	global_load_ushort v150, v[150:151], off
	s_or_b32 s44, s26, 9
	global_load_ushort v151, v[152:153], off
	v_mad_u64_u32 v[152:153], s[0:1], s0, v165, v[68:69]
	s_max_i32 s0, s44, 0
	s_nop 0
	v_mad_u64_u32 v[154:155], s[0:1], s0, v165, v[68:69]
	s_or_b32 s45, s26, 10
	s_max_i32 s0, s45, 0
	global_load_ushort v152, v[152:153], off
	s_or_b32 s46, s26, 11
	global_load_ushort v153, v[154:155], off
	v_mad_u64_u32 v[154:155], s[0:1], s0, v165, v[68:69]
	s_max_i32 s0, s46, 0
	s_nop 0
	v_mad_u64_u32 v[156:157], s[0:1], s0, v165, v[68:69]
	s_or_b32 s47, s26, 12
	s_max_i32 s0, s47, 0
	global_load_ushort v154, v[154:155], off
	s_or_b32 s48, s26, 13
	global_load_ushort v155, v[156:157], off
	v_mad_u64_u32 v[156:157], s[0:1], s0, v165, v[68:69]
	s_max_i32 s0, s48, 0
	s_nop 0
	v_mad_u64_u32 v[170:171], s[0:1], s0, v165, v[68:69]
	s_or_b32 s49, s26, 14
	s_max_i32 s0, s49, 0
	global_load_ushort v156, v[156:157], off
	s_or_b32 s50, s26, 15
	global_load_ushort v157, v[170:171], off
	v_mad_u64_u32 v[170:171], s[0:1], s0, v165, v[68:69]
	s_max_i32 s0, s50, 0
	s_nop 0
	v_mad_u64_u32 v[172:173], s[0:1], s0, v165, v[68:69]
	global_load_ushort v170, v[170:171], off
	v_mad_i64_i32 v[174:175], s[0:1], s25, v165, v[68:69]
	global_load_ushort v171, v[172:173], off
	v_mad_i64_i32 v[172:173], s[0:1], s26, v165, v[68:69]
	global_load_ushort v172, v[172:173], off offset:1536
	v_mad_i64_i32 v[176:177], s[0:1], s38, v165, v[68:69]
	global_load_ushort v173, v[174:175], off offset:1536
	v_mad_i64_i32 v[174:175], s[0:1], s27, v165, v[68:69]
	global_load_ushort v174, v[174:175], off offset:1536
	v_mad_i64_i32 v[178:179], s[0:1], s40, v165, v[68:69]
	global_load_ushort v175, v[176:177], off offset:1536
	v_mad_i64_i32 v[176:177], s[0:1], s39, v165, v[68:69]
	global_load_ushort v176, v[176:177], off offset:1536
	v_mad_i64_i32 v[180:181], s[0:1], s42, v165, v[68:69]
	global_load_ushort v177, v[178:179], off offset:1536
	v_mad_i64_i32 v[178:179], s[0:1], s41, v165, v[68:69]
	global_load_ushort v178, v[178:179], off offset:1536
	v_mad_i64_i32 v[182:183], s[0:1], s44, v165, v[68:69]
	global_load_ushort v179, v[180:181], off offset:1536
	v_mad_i64_i32 v[180:181], s[0:1], s43, v165, v[68:69]
	global_load_ushort v180, v[180:181], off offset:1536
	v_mad_i64_i32 v[184:185], s[0:1], s46, v165, v[68:69]
	global_load_ushort v181, v[182:183], off offset:1536
	v_mad_i64_i32 v[182:183], s[0:1], s45, v165, v[68:69]
	global_load_ushort v182, v[182:183], off offset:1536
	v_mad_i64_i32 v[186:187], s[0:1], s48, v165, v[68:69]
	global_load_ushort v183, v[184:185], off offset:1536
	v_mad_i64_i32 v[184:185], s[0:1], s47, v165, v[68:69]
	global_load_ushort v184, v[184:185], off offset:1536
	v_readlane_b32 s94, v242, 38
	global_load_ushort v185, v[186:187], off offset:1536
	v_mad_i64_i32 v[186:187], s[0:1], s49, v165, v[68:69]
	v_mad_i64_i32 v[68:69], s[0:1], s50, v165, v[68:69]
	global_load_ushort v186, v[186:187], off offset:1536
	v_readlane_b32 s38, v242, 57
	global_load_ushort v187, v[68:69], off offset:1536
	v_readlane_b32 s95, v242, 39
	v_readlane_b32 s39, v242, 58
.LBB0_94:
	s_lshl_b32 s0, s21, 7
	s_add_i32 s26, s0, s77
	s_cmp_gt_i32 s26, 2
	v_lshlrev_b32_e32 v68, 16, v206
	s_cselect_b64 vcc, -1, 0
	s_cmp_gt_i32 s26, 1
	v_cndmask_b32_e32 v68, 0, v68, vcc
	v_lshlrev_b32_e32 v69, 16, v205
	s_cselect_b64 vcc, -1, 0
	s_cmp_gt_i32 s26, 0
	v_cndmask_b32_e32 v69, 0, v69, vcc
	v_lshlrev_b32_e32 v204, 16, v204
	s_cselect_b64 vcc, -1, 0
	v_cndmask_b32_e32 v204, 0, v204, vcc
	v_lshlrev_b32_e32 v203, 16, v203
	v_lshlrev_b32_e32 v202, 16, v202
	v_lshlrev_b32_e32 v201, 16, v201
	v_lshlrev_b32_e32 v200, 16, v200
	v_lshlrev_b32_e32 v206, 16, v199
	v_lshlrev_b32_e32 v198, 16, v198
	v_lshlrev_b32_e32 v197, 16, v197
	v_lshlrev_b32_e32 v209, 16, v196
	v_lshlrev_b32_e32 v195, 16, v195
	v_lshlrev_b32_e32 v194, 16, v194
	v_lshlrev_b32_e32 v210, 16, v193
	v_lshlrev_b32_e32 v211, 16, v192
	v_lshlrev_b32_e32 v191, 16, v191
	v_lshlrev_b32_e32 v212, 16, v190
	v_fma_f32 v226, v68, v81, v117
	v_fmac_f32_e32 v226, v69, v114
	v_fma_f32 v190, v69, v81, v117
	v_fmac_f32_e32 v226, v204, v115
	v_fmac_f32_e32 v190, v204, v114
	v_fma_f32 v193, v204, v81, v117
	v_fmac_f32_e32 v226, v203, v116
	v_cvt_pk_bf16_f32 v68, v226, v129
	v_fmac_f32_e32 v190, v203, v115
	v_fmac_f32_e32 v193, v203, v114
	v_fma_f32 v196, v203, v81, v117
	ds_write_b16 v72, v68
	v_fmac_f32_e32 v190, v202, v116
	v_cvt_pk_bf16_f32 v68, v190, v129
	v_fmac_f32_e32 v193, v202, v115
	v_fmac_f32_e32 v196, v202, v114
	v_fma_f32 v199, v202, v81, v117
	ds_write_b16 v72, v68 offset:144
	v_fmac_f32_e32 v193, v201, v116
	v_cvt_pk_bf16_f32 v68, v193, v129
	v_fmac_f32_e32 v196, v201, v115
	v_fmac_f32_e32 v199, v201, v114
	v_fma_f32 v202, v201, v81, v117
	ds_write_b16 v72, v68 offset:288
	v_fmac_f32_e32 v196, v200, v116
	v_cvt_pk_bf16_f32 v68, v196, v129
	v_fmac_f32_e32 v199, v200, v115
	v_fmac_f32_e32 v202, v200, v114
	v_fma_f32 v205, v200, v81, v117
	ds_write_b16 v72, v68 offset:432
	v_fmac_f32_e32 v199, v206, v116
	v_cvt_pk_bf16_f32 v68, v199, v129
	v_fmac_f32_e32 v202, v206, v115
	v_fmac_f32_e32 v205, v206, v114
	v_fma_f32 v208, v206, v81, v117
	ds_write_b16 v72, v68 offset:576
	v_fmac_f32_e32 v202, v198, v116
	v_cvt_pk_bf16_f32 v68, v202, v129
	v_fmac_f32_e32 v205, v198, v115
	v_fmac_f32_e32 v208, v198, v114
	v_fma_f32 v207, v198, v81, v117
	ds_write_b16 v72, v68 offset:720
	v_fmac_f32_e32 v205, v197, v116
	v_cvt_pk_bf16_f32 v68, v205, v129
	v_fmac_f32_e32 v208, v197, v115
	v_fmac_f32_e32 v207, v197, v114
	v_fma_f32 v204, v197, v81, v117
	ds_write_b16 v72, v68 offset:864
	v_fmac_f32_e32 v208, v209, v116
	v_cvt_pk_bf16_f32 v68, v208, v129
	v_fmac_f32_e32 v207, v209, v115
	v_fmac_f32_e32 v204, v209, v114
	v_fma_f32 v201, v209, v81, v117
	ds_write_b16 v72, v68 offset:1008
	v_fmac_f32_e32 v207, v195, v116
	v_cvt_pk_bf16_f32 v68, v207, v129
	v_fmac_f32_e32 v204, v195, v115
	v_fmac_f32_e32 v201, v195, v114
	v_fma_f32 v198, v195, v81, v117
	ds_write_b16 v72, v68 offset:1152
	v_fmac_f32_e32 v204, v194, v116
	v_cvt_pk_bf16_f32 v68, v204, v129
	v_fmac_f32_e32 v201, v194, v115
	v_fmac_f32_e32 v198, v194, v114
	v_fma_f32 v195, v194, v81, v117
	ds_write_b16 v72, v68 offset:1296
	v_fmac_f32_e32 v201, v210, v116
	v_cvt_pk_bf16_f32 v68, v201, v129
	v_fmac_f32_e32 v198, v210, v115
	v_fmac_f32_e32 v195, v210, v114
	v_fma_f32 v192, v210, v81, v117
	s_cmp_gt_i32 s26, -15
	ds_write_b16 v72, v68 offset:1440
	v_fmac_f32_e32 v198, v211, v116
	v_cvt_pk_bf16_f32 v68, v198, v129
	v_fmac_f32_e32 v195, v211, v115
	v_fmac_f32_e32 v192, v211, v114
	v_fma_f32 v69, v211, v81, v117
	v_lshlrev_b32_e32 v189, 16, v189
	s_cselect_b64 vcc, -1, 0
	ds_write_b16 v72, v68 offset:1584
	v_fmac_f32_e32 v195, v191, v116
	v_cvt_pk_bf16_f32 v68, v195, v129
	v_fmac_f32_e32 v192, v191, v115
	v_fmac_f32_e32 v69, v191, v114
	v_cndmask_b32_e32 v189, 0, v189, vcc
	ds_write_b16 v72, v68 offset:1728
	v_fmac_f32_e32 v192, v212, v116
	v_cvt_pk_bf16_f32 v68, v192, v129
	v_fmac_f32_e32 v69, v212, v115
	ds_write_b16 v72, v68 offset:1872
	v_fmac_f32_e32 v69, v189, v116
	v_cvt_pk_bf16_f32 v68, v69, v129
	s_cmp_gt_i32 s26, -16
	ds_write_b16 v72, v68 offset:2016
	v_fma_f32 v68, v191, v81, v117
	v_lshlrev_b32_e32 v188, 16, v188
	s_cselect_b64 vcc, -1, 0
	v_fmac_f32_e32 v68, v212, v114
	v_cndmask_b32_e32 v188, 0, v188, vcc
	v_fmac_f32_e32 v68, v189, v115
	v_fmac_f32_e32 v68, v188, v116
	v_cvt_pk_bf16_f32 v188, v68, v129
	ds_write_b16 v72, v188 offset:2160
	s_waitcnt lgkmcnt(0)
	ds_read_b128 v[210:213], v112
	ds_read_b128 v[214:217], v112 offset:64
	s_waitcnt lgkmcnt(0)
	v_mfma_f32_16x16x32_bf16 v[218:221], v[210:213], v[0:3], 0
	v_add_u32_e32 v188, 0x800, v113
	v_add_u32_e32 v189, 0xc00, v113
	v_mfma_f32_16x16x32_bf16 v[222:225], v[210:213], v[8:11], 0
	v_mfma_f32_16x16x32_bf16 v[218:221], v[214:217], v[4:7], v[218:221]
	v_mfma_f32_16x16x32_bf16 v[222:225], v[214:217], v[12:15], v[222:225]
	s_nop 7
	ds_write2_b32 v188, v218, v222 offset0:64 offset1:80
	ds_write2_b32 v188, v219, v223 offset0:132 offset1:148
	ds_write2_b32 v188, v220, v224 offset0:200 offset1:216
	ds_write2_b32 v189, v221, v225 offset0:12 offset1:28
	v_mfma_f32_16x16x32_bf16 v[218:221], v[210:213], v[16:19], 0
	v_mfma_f32_16x16x32_bf16 v[222:225], v[210:213], v[24:27], 0
	v_mfma_f32_16x16x32_bf16 v[218:221], v[214:217], v[20:23], v[218:221]
	v_mfma_f32_16x16x32_bf16 v[222:225], v[214:217], v[28:31], v[222:225]
	s_nop 7
	ds_write2_b32 v188, v218, v222 offset0:96 offset1:112
	ds_write2_b32 v188, v219, v223 offset0:164 offset1:180
	ds_write2_b32 v188, v220, v224 offset0:232 offset1:248
	ds_write2_b32 v189, v221, v225 offset0:44 offset1:60
	v_mfma_f32_16x16x32_bf16 v[218:221], v[210:213], v[32:35], 0
	v_add_u32_e32 v188, 0x1800, v113
	v_add_u32_e32 v189, 0x1c00, v113
	v_mfma_f32_16x16x32_bf16 v[222:225], v[210:213], v[40:43], 0
	v_mfma_f32_16x16x32_bf16 v[218:221], v[214:217], v[36:39], v[218:221]
	v_mfma_f32_16x16x32_bf16 v[222:225], v[214:217], v[44:47], v[222:225]
	s_nop 7
	ds_write2_b32 v188, v218, v222 offset0:128 offset1:144
	ds_write2_b32 v188, v219, v223 offset0:196 offset1:212
	ds_write2_b32 v189, v220, v224 offset0:8 offset1:24
	ds_write2_b32 v189, v221, v225 offset0:76 offset1:92
	v_mfma_f32_16x16x32_bf16 v[218:221], v[210:213], v[48:51], 0
	v_mfma_f32_16x16x32_bf16 v[210:213], v[210:213], v[56:59], 0
	v_mfma_f32_16x16x32_bf16 v[218:221], v[214:217], v[52:55], v[218:221]
	v_mfma_f32_16x16x32_bf16 v[210:213], v[214:217], v[60:63], v[210:213]
	s_nop 7
	ds_write2_b32 v188, v218, v210 offset0:160 offset1:176
	ds_write2_b32 v188, v219, v211 offset0:228 offset1:244
	ds_write2_b32 v189, v220, v212 offset0:40 offset1:56
	ds_write2_b32 v189, v221, v213 offset0:108 offset1:124
	s_waitcnt lgkmcnt(0)
	v_add_u32_e32 v188, 0x800, v73
	ds_read2_b32 v[210:211], v188 offset0:64 offset1:132
	v_add_u32_e32 v189, 0x1800, v73
	ds_read2_b32 v[212:213], v189 offset0:128 offset1:196
	v_add_u32_e32 v214, 0x2000, v73
	s_waitcnt lgkmcnt(1)
	v_fmamk_f32 v188, v210, 0xbfb8aa3b, v131
	v_exp_f32_e32 v188, v188
	s_waitcnt lgkmcnt(0)
	v_fmamk_f32 v189, v212, 0xbfb8aa3b, v67
	v_exp_f32_e32 v189, v189
	v_add_f32_e32 v188, 1.0, v188
	v_rcp_f32_e32 v188, v188
	v_add_f32_e32 v189, 1.0, v189
	v_rcp_f32_e32 v189, v189
	v_mul_f32_e32 v188, v66, v188
	v_exp_f32_e32 v188, v188
	s_nop 0
	v_fma_f32 v191, -v188, v188, 1.0
	v_max_f32_e32 v191, 0, v191
	v_sqrt_f32_e32 v191, v191
	s_nop 0
	v_mul_f32_e32 v189, v189, v191
	v_fmamk_f32 v191, v211, 0xbfb8aa3b, v131
	v_exp_f32_e32 v191, v191
	v_fmamk_f32 v194, v213, 0xbfb8aa3b, v67
	v_exp_f32_e32 v194, v194
	v_mul_f32_e32 v189, v226, v189
	v_add_f32_e32 v191, 1.0, v191
	v_rcp_f32_e32 v191, v191
	v_add_f32_e32 v194, 1.0, v194
	v_rcp_f32_e32 v194, v194
	v_fmac_f32_e32 v189, 0, v188
	v_mul_f32_e32 v191, v66, v191
	v_exp_f32_e32 v191, v191
	s_nop 0
	v_fma_f32 v197, -v191, v191, 1.0
	v_max_f32_e32 v197, 0, v197
	v_sqrt_f32_e32 v197, v197
	s_nop 0
	v_mul_f32_e32 v194, v194, v197
	v_mul_f32_e32 v190, v190, v194
	v_add_u32_e32 v194, 0xa00, v73
	ds_read2_b32 v[210:211], v194 offset0:72 offset1:140
	v_add_u32_e32 v200, 0x1c00, v73
	ds_read2_b32 v[212:213], v200 offset0:8 offset1:76
	v_fmac_f32_e32 v190, v191, v189
	v_mul_f32_e32 v191, v188, v191
	s_waitcnt lgkmcnt(1)
	v_fmamk_f32 v194, v210, 0xbfb8aa3b, v131
	v_exp_f32_e32 v194, v194
	s_waitcnt lgkmcnt(0)
	v_fmamk_f32 v197, v212, 0xbfb8aa3b, v67
	v_exp_f32_e32 v197, v197
	v_add_f32_e32 v194, 1.0, v194
	v_rcp_f32_e32 v194, v194
	v_add_f32_e32 v197, 1.0, v197
	v_rcp_f32_e32 v197, v197
	v_mul_f32_e32 v194, v66, v194
	v_exp_f32_e32 v194, v194
	s_nop 0
	v_fma_f32 v203, -v194, v194, 1.0
	v_max_f32_e32 v203, 0, v203
	v_sqrt_f32_e32 v203, v203
	s_nop 0
	v_mul_f32_e32 v197, v197, v203
	v_mul_f32_e32 v193, v193, v197
	v_fmamk_f32 v197, v211, 0xbfb8aa3b, v131
	v_exp_f32_e32 v197, v197
	v_fmamk_f32 v203, v213, 0xbfb8aa3b, v67
	v_exp_f32_e32 v203, v203
	ds_read2_b32 v[212:213], v200 offset0:144 offset1:212
	v_add_f32_e32 v197, 1.0, v197
	v_rcp_f32_e32 v197, v197
	v_add_f32_e32 v203, 1.0, v203
	v_rcp_f32_e32 v203, v203
	s_waitcnt lgkmcnt(0)
	v_fmamk_f32 v200, v212, 0xbfb8aa3b, v67
	v_mul_f32_e32 v197, v66, v197
	v_exp_f32_e32 v197, v197
	v_exp_f32_e32 v200, v200
	v_fmac_f32_e32 v193, v194, v190
	v_mul_f32_e32 v194, v191, v194
	v_fma_f32 v206, -v197, v197, 1.0
	v_max_f32_e32 v206, 0, v206
	v_add_f32_e32 v200, 1.0, v200
	v_sqrt_f32_e32 v206, v206
	s_nop 0
	v_rcp_f32_e32 v200, v200
	s_nop 0
	v_mul_f32_e32 v203, v203, v206
	v_mul_f32_e32 v196, v196, v203
	v_add_u32_e32 v203, 0xc00, v73
	ds_read2_b32 v[210:211], v203 offset0:80 offset1:148
	v_fmac_f32_e32 v196, v197, v193
	v_mul_f32_e32 v197, v194, v197
	s_waitcnt lgkmcnt(0)
	v_fmamk_f32 v203, v210, 0xbfb8aa3b, v131
	v_exp_f32_e32 v203, v203
	s_nop 0
	v_add_f32_e32 v203, 1.0, v203
	v_rcp_f32_e32 v203, v203
	s_nop 0
	v_mul_f32_e32 v203, v66, v203
	v_exp_f32_e32 v203, v203
	s_nop 0
	v_fma_f32 v206, -v203, v203, 1.0
	v_max_f32_e32 v206, 0, v206
	v_sqrt_f32_e32 v206, v206
	s_nop 0
	v_mul_f32_e32 v200, v200, v206
	v_mul_f32_e32 v199, v199, v200
	v_fmac_f32_e32 v199, v203, v196
	v_mul_f32_e32 v200, v197, v203
	v_fmamk_f32 v203, v211, 0xbfb8aa3b, v131
	v_exp_f32_e32 v203, v203
	v_fmamk_f32 v206, v213, 0xbfb8aa3b, v67
	v_exp_f32_e32 v206, v206
	v_add_f32_e32 v203, 1.0, v203
	v_rcp_f32_e32 v203, v203
	v_add_f32_e32 v206, 1.0, v206
	v_rcp_f32_e32 v206, v206
	v_mul_f32_e32 v203, v66, v203
	v_exp_f32_e32 v203, v203
	s_nop 0
	v_fma_f32 v209, -v203, v203, 1.0
	v_max_f32_e32 v209, 0, v209
	v_sqrt_f32_e32 v209, v209
	s_nop 0
	ds_read2_b32 v[212:213], v214 offset0:24 offset1:92
	v_mul_f32_e32 v206, v206, v209
	v_mul_f32_e32 v202, v202, v206
	v_add_u32_e32 v206, 0xe00, v73
	ds_read2_b32 v[210:211], v206 offset0:88 offset1:156
	s_waitcnt lgkmcnt(1)
	v_fmamk_f32 v209, v212, 0xbfb8aa3b, v67
	v_exp_f32_e32 v209, v209
	v_fmac_f32_e32 v202, v203, v199
	v_mul_f32_e32 v203, v200, v203
	s_waitcnt lgkmcnt(0)
	v_fmamk_f32 v206, v210, 0xbfb8aa3b, v131
	v_exp_f32_e32 v206, v206
	v_add_f32_e32 v209, 1.0, v209
	v_rcp_f32_e32 v209, v209
	v_add_f32_e32 v206, 1.0, v206
	v_rcp_f32_e32 v206, v206
	s_nop 0
	v_mul_f32_e32 v206, v66, v206
	v_exp_f32_e32 v206, v206
	s_nop 0
	v_fma_f32 v210, -v206, v206, 1.0
	v_max_f32_e32 v210, 0, v210
	v_sqrt_f32_e32 v210, v210
	s_nop 0
	v_mul_f32_e32 v209, v209, v210
	v_mul_f32_e32 v205, v205, v209
	v_fmamk_f32 v209, v211, 0xbfb8aa3b, v131
	v_exp_f32_e32 v209, v209
	v_fmamk_f32 v210, v213, 0xbfb8aa3b, v67
	v_exp_f32_e32 v210, v210
	v_fmac_f32_e32 v205, v206, v202
	v_add_f32_e32 v209, 1.0, v209
	v_rcp_f32_e32 v209, v209
	v_add_f32_e32 v210, 1.0, v210
	v_rcp_f32_e32 v210, v210
	v_mul_f32_e32 v206, v203, v206
	v_mul_f32_e32 v209, v66, v209
	v_exp_f32_e32 v209, v209
	s_nop 0
	v_fma_f32 v211, -v209, v209, 1.0
	v_max_f32_e32 v211, 0, v211
	v_sqrt_f32_e32 v211, v211
	s_nop 0
	v_mul_f32_e32 v210, v210, v211
	v_mul_f32_e32 v208, v208, v210
	v_add_u32_e32 v210, 0x1000, v73
	ds_read2_b32 v[210:211], v210 offset0:96 offset1:164
	ds_read2_b32 v[212:213], v214 offset0:160 offset1:228
	v_fmac_f32_e32 v208, v209, v205
	v_mul_f32_e32 v209, v206, v209
	s_waitcnt lgkmcnt(1)
	v_fmamk_f32 v210, v210, 0xbfb8aa3b, v131
	v_exp_f32_e32 v210, v210
	v_fmamk_f32 v211, v211, 0xbfb8aa3b, v131
	v_exp_f32_e32 v211, v211
	s_waitcnt lgkmcnt(0)
	v_fmamk_f32 v212, v212, 0xbfb8aa3b, v67
	v_add_f32_e32 v210, 1.0, v210
	v_rcp_f32_e32 v210, v210
	v_exp_f32_e32 v212, v212
	v_add_f32_e32 v211, 1.0, v211
	v_rcp_f32_e32 v211, v211
	v_mul_f32_e32 v210, v66, v210
	v_exp_f32_e32 v210, v210
	v_add_f32_e32 v212, 1.0, v212
	v_rcp_f32_e32 v212, v212
	v_mul_f32_e32 v211, v66, v211
	v_fma_f32 v214, -v210, v210, 1.0
	v_max_f32_e32 v214, 0, v214
	v_exp_f32_e32 v211, v211
	s_nop 0
	v_sqrt_f32_e32 v214, v214
	s_nop 0
	v_mul_f32_e32 v212, v212, v214
	v_mul_f32_e32 v207, v207, v212
	v_fmamk_f32 v212, v213, 0xbfb8aa3b, v67
	v_fma_f32 v213, -v211, v211, 1.0
	v_max_f32_e32 v213, 0, v213
	v_exp_f32_e32 v212, v212
	s_nop 0
	v_sqrt_f32_e32 v213, v213
	s_nop 0
	v_fmac_f32_e32 v207, v210, v208
	v_add_f32_e32 v212, 1.0, v212
	v_rcp_f32_e32 v212, v212
	s_nop 0
	v_mul_f32_e32 v210, v209, v210
	v_add_u32_e32 v216, 0x2400, v73
	v_mul_f32_e32 v212, v212, v213
	v_mul_f32_e32 v204, v204, v212
	v_add_u32_e32 v212, 0x1200, v73
	ds_read2_b32 v[212:213], v212 offset0:104 offset1:172
	ds_read2_b32 v[214:215], v216 offset0:40 offset1:108
	v_fmac_f32_e32 v204, v211, v207
	v_mul_f32_e32 v211, v210, v211
	s_waitcnt lgkmcnt(1)
	v_fmamk_f32 v212, v212, 0xbfb8aa3b, v131
	v_exp_f32_e32 v212, v212
	v_fmamk_f32 v213, v213, 0xbfb8aa3b, v131
	v_exp_f32_e32 v213, v213
	s_waitcnt lgkmcnt(0)
	v_fmamk_f32 v214, v214, 0xbfb8aa3b, v67
	v_add_f32_e32 v212, 1.0, v212
	v_rcp_f32_e32 v212, v212
	v_exp_f32_e32 v214, v214
	v_add_f32_e32 v213, 1.0, v213
	v_rcp_f32_e32 v213, v213
	v_mul_f32_e32 v212, v66, v212
	v_exp_f32_e32 v212, v212
	v_add_f32_e32 v214, 1.0, v214
	v_rcp_f32_e32 v214, v214
	v_mul_f32_e32 v213, v66, v213
	v_fma_f32 v217, -v212, v212, 1.0
	v_max_f32_e32 v217, 0, v217
	v_exp_f32_e32 v213, v213
	s_nop 0
	v_sqrt_f32_e32 v217, v217
	s_nop 0
	v_mul_f32_e32 v214, v214, v217
	v_mul_f32_e32 v201, v201, v214
	v_fmamk_f32 v214, v215, 0xbfb8aa3b, v67
	v_fma_f32 v215, -v213, v213, 1.0
	v_max_f32_e32 v215, 0, v215
	v_exp_f32_e32 v214, v214
	s_nop 0
	v_sqrt_f32_e32 v215, v215
	s_nop 0
	v_fmac_f32_e32 v201, v212, v204
	v_add_f32_e32 v214, 1.0, v214
	v_rcp_f32_e32 v214, v214
	s_nop 0
	v_mul_f32_e32 v212, v211, v212
	v_mul_f32_e32 v214, v214, v215
	v_mul_f32_e32 v198, v198, v214
	v_add_u32_e32 v214, 0x1400, v73
	ds_read2_b32 v[214:215], v214 offset0:112 offset1:180
	ds_read2_b32 v[216:217], v216 offset0:176 offset1:244
	v_fmac_f32_e32 v198, v213, v201
	v_mul_f32_e32 v213, v212, v213
	s_waitcnt lgkmcnt(1)
	v_fmamk_f32 v214, v214, 0xbfb8aa3b, v131
	v_exp_f32_e32 v214, v214
	v_fmamk_f32 v215, v215, 0xbfb8aa3b, v131
	v_exp_f32_e32 v215, v215
	s_waitcnt lgkmcnt(0)
	v_fmamk_f32 v216, v216, 0xbfb8aa3b, v67
	v_add_f32_e32 v214, 1.0, v214
	v_rcp_f32_e32 v214, v214
	v_exp_f32_e32 v216, v216
	v_add_f32_e32 v215, 1.0, v215
	v_rcp_f32_e32 v215, v215
	v_mul_f32_e32 v214, v66, v214
	v_exp_f32_e32 v214, v214
	v_add_f32_e32 v216, 1.0, v216
	v_rcp_f32_e32 v216, v216
	v_mul_f32_e32 v215, v66, v215
	v_fma_f32 v218, -v214, v214, 1.0
	v_max_f32_e32 v218, 0, v218
	v_exp_f32_e32 v215, v215
	s_nop 0
	v_sqrt_f32_e32 v218, v218
	s_nop 0
	v_mul_f32_e32 v216, v216, v218
	v_mul_f32_e32 v195, v195, v216
	v_fmamk_f32 v216, v217, 0xbfb8aa3b, v67
	v_fma_f32 v217, -v215, v215, 1.0
	v_max_f32_e32 v217, 0, v217
	v_exp_f32_e32 v216, v216
	s_nop 0
	v_sqrt_f32_e32 v217, v217
	s_nop 0
	v_fmac_f32_e32 v195, v214, v198
	v_add_f32_e32 v216, 1.0, v216
	v_rcp_f32_e32 v216, v216
	s_nop 0
	v_mul_f32_e32 v214, v213, v214
	v_mul_f32_e32 v216, v216, v217
	v_mul_f32_e32 v192, v192, v216
	v_add_u32_e32 v216, 0x1600, v73
	ds_read2_b32 v[218:219], v216 offset0:120 offset1:188
	v_add_u32_e32 v217, 0x2800, v73
	ds_read2_b32 v[220:221], v217 offset0:56 offset1:124
	v_fmac_f32_e32 v192, v215, v195
	v_mul_f32_e32 v215, v214, v215
	s_waitcnt lgkmcnt(1)
	v_fmamk_f32 v216, v218, 0xbfb8aa3b, v131
	v_exp_f32_e32 v216, v216
	s_waitcnt lgkmcnt(0)
	v_fmamk_f32 v217, v220, 0xbfb8aa3b, v67
	v_exp_f32_e32 v217, v217
	v_add_f32_e32 v216, 1.0, v216
	v_rcp_f32_e32 v216, v216
	v_add_f32_e32 v217, 1.0, v217
	v_rcp_f32_e32 v217, v217
	v_mul_f32_e32 v216, v66, v216
	v_exp_f32_e32 v218, v216
	s_nop 0
	v_fma_f32 v216, -v218, v218, 1.0
	v_max_f32_e32 v216, 0, v216
	v_sqrt_f32_e32 v216, v216
	s_nop 0
	v_mul_f32_e32 v216, v217, v216
	v_mul_f32_e32 v216, v69, v216
	v_fmamk_f32 v69, v219, 0xbfb8aa3b, v131
	v_exp_f32_e32 v69, v69
	v_fmac_f32_e32 v216, v218, v192
	v_mul_f32_e32 v217, v215, v218
	v_fmamk_f32 v218, v221, 0xbfb8aa3b, v67
	v_add_f32_e32 v69, 1.0, v69
	v_rcp_f32_e32 v69, v69
	v_exp_f32_e32 v218, v218
	v_mul_f32_e32 v69, v66, v69
	v_exp_f32_e32 v69, v69
	v_add_f32_e32 v218, 1.0, v218
	v_rcp_f32_e32 v218, v218
	v_fma_f32 v219, -v69, v69, 1.0
	v_max_f32_e32 v219, 0, v219
	v_sqrt_f32_e32 v219, v219
	s_nop 0
	s_mov_b32 s0, s91
	v_mul_f32_e32 v218, v218, v219
	v_mul_f32_e32 v218, v68, v218
	v_fmac_f32_e32 v218, v69, v216
	v_mul_f32_e32 v219, v217, v69
	ds_write2st64_b32 v140, v219, v218 offset1:1
	s_waitcnt lgkmcnt(0)
	s_barrier
	ds_read_b32 v140, v71
	s_andn2_b64 vcc, exec, s[10:11]
	v_mov_b32_e32 v68, v74
	s_cbranch_vccnz .LBB0_96

.LBB0_125:
	s_add_i32 s10, s10, 1
	s_cmp_ge_i32 s10, s11
	s_cselect_b64 s[6:7], -1, 0
	s_and_b64 vcc, exec, s[6:7]
	s_waitcnt vmcnt(0)
	s_cbranch_vccnz .LBB0_127
	s_ashr_i32 s0, s10, 5
	s_mul_hi_i32 s1, s0, 0x2aaaaaab
	s_lshr_b32 s5, s1, 31
	s_ashr_i32 s1, s1, 1
	s_add_i32 s1, s1, s5
	s_mul_i32 s5, s1, -12
	s_add_i32 s5, s5, s0
	s_add_i32 s0, s15, 0x80
	s_and_b32 s17, s0, 0xf80
	s_mul_hi_i32 s0, s1, 0x1e00000
	s_mul_i32 s1, s1, 0x1e00000
	s_add_u32 s18, s33, s1
	s_addc_u32 s19, s68, s0
	s_lshl_b32 s0, s5, 6
	s_ashr_i32 s1, s0, 31
	s_lshl_b64 s[0:1], s[0:1], 1
	s_add_u32 s0, s18, s0
	s_addc_u32 s1, s19, s1
	v_lshl_add_u64 v[138:139], s[0:1], 0, v[128:129]
	s_mov_b64 s[0:1], 0x1200
	s_add_i32 s5, s17, s13
	v_lshl_add_u64 v[170:171], v[138:139], 0, s[0:1]
	s_max_i32 s0, s5, 0
	v_mad_u64_u32 v[138:139], s[0:1], s0, v165, v[170:171]
	s_max_i32 s0, s5, -1
	s_add_i32 s0, s0, 1
	global_load_ushort v131, v[138:139], off
	v_mad_u64_u32 v[138:139], s[0:1], s0, v165, v[170:171]
	s_or_b32 s0, s5, 2
	s_max_i32 s0, s0, 0
	v_mad_u64_u32 v[142:143], s[0:1], s0, v165, v[170:171]
	s_add_i32 s17, s17, s12
	s_max_i32 s0, s17, 0
	global_load_ushort v138, v[138:139], off
	v_readlane_b32 s18, v242, 44
	global_load_ushort v139, v[142:143], off
	v_mad_u64_u32 v[142:143], s[0:1], s0, v165, v[170:171]
	s_max_i32 s0, s5, -4
	s_add_i32 s0, s0, 4
	v_mad_u64_u32 v[144:145], s[0:1], s0, v165, v[170:171]
	s_max_i32 s0, s5, -5
	s_add_i32 s0, s0, 5
	global_load_ushort v142, v[142:143], off
	v_readlane_b32 s19, v242, 45
	global_load_ushort v143, v[144:145], off
	v_mad_u64_u32 v[144:145], s[0:1], s0, v165, v[170:171]
	s_max_i32 s0, s5, -6
	s_add_i32 s0, s0, 6
	v_mad_u64_u32 v[146:147], s[0:1], s0, v165, v[170:171]
	s_max_i32 s0, s5, -7
	s_add_i32 s0, s0, 7
	global_load_ushort v144, v[144:145], off
	s_nop 0
	global_load_ushort v145, v[146:147], off
	v_mad_u64_u32 v[146:147], s[0:1], s0, v165, v[170:171]
	s_max_i32 s0, s5, -8
	s_add_i32 s0, s0, 8
	v_mad_u64_u32 v[148:149], s[0:1], s0, v165, v[170:171]
	s_max_i32 s0, s5, -9
	s_add_i32 s0, s0, 9
	global_load_ushort v146, v[146:147], off
	s_nop 0
	global_load_ushort v147, v[148:149], off
	v_mad_u64_u32 v[148:149], s[0:1], s0, v165, v[170:171]
	s_max_i32 s0, s5, -10
	s_add_i32 s0, s0, 10
	v_mad_u64_u32 v[150:151], s[0:1], s0, v165, v[170:171]
	s_max_i32 s0, s5, -11
	s_add_i32 s0, s0, 11
	global_load_ushort v148, v[148:149], off
	s_nop 0
	global_load_ushort v149, v[150:151], off
	v_mad_u64_u32 v[150:151], s[0:1], s0, v165, v[170:171]
	s_max_i32 s0, s5, -12
	s_add_i32 s0, s0, 12
	v_mad_u64_u32 v[152:153], s[0:1], s0, v165, v[170:171]
	s_max_i32 s0, s5, -13
	s_add_i32 s0, s0, 13
	global_load_ushort v150, v[150:151], off
	s_nop 0
	global_load_ushort v151, v[152:153], off
	v_mad_u64_u32 v[152:153], s[0:1], s0, v165, v[170:171]
	s_max_i32 s0, s5, -14
	s_add_i32 s0, s0, 14
	v_mad_u64_u32 v[154:155], s[0:1], s0, v165, v[170:171]
	s_max_i32 s0, s5, -15
	s_add_i32 s0, s0, 15
	global_load_ushort v152, v[152:153], off
	s_nop 0
	global_load_ushort v153, v[154:155], off
	v_mad_u64_u32 v[154:155], s[0:1], s0, v165, v[170:171]
	s_max_i32 s0, s5, -16
	s_add_i32 s0, s0, 16
	v_mad_u64_u32 v[156:157], s[0:1], s0, v165, v[170:171]
	s_max_i32 s0, s5, 0xffffffef
	s_add_i32 s0, s0, 17
	global_load_ushort v154, v[154:155], off
	s_nop 0
	global_load_ushort v155, v[156:157], off
	v_mad_u64_u32 v[156:157], s[0:1], s0, v165, v[170:171]
	s_max_i32 s0, s5, 0xffffffee
	s_add_i32 s0, s0, 18
	v_mad_u64_u32 v[170:171], s[0:1], s0, v165, v[170:171]
	global_load_ushort v156, v[156:157], off
	s_nop 0
	global_load_ushort v157, v[170:171], off

.Lcvf_a_done:
	s_and_b32 s17, s15, 0xf80
	s_add_i32 s0, s17, s12
	s_cmp_gt_i32 s0, 2
	v_lshlrev_b32_e32 v137, 16, v137
	s_cselect_b64 vcc, -1, 0
	s_cmp_gt_i32 s0, 1
	v_cndmask_b32_e32 v137, 0, v137, vcc
	v_lshlrev_b32_e32 v136, 16, v136
	s_cselect_b64 vcc, -1, 0
	s_cmp_gt_i32 s0, 0
	v_cndmask_b32_e32 v136, 0, v136, vcc
	v_lshlrev_b32_e32 v135, 16, v135
	s_cselect_b64 vcc, -1, 0
	v_cndmask_b32_e32 v135, 0, v135, vcc
	v_lshlrev_b32_e32 v134, 16, v134
	v_lshlrev_b32_e32 v170, 16, v127
	v_lshlrev_b32_e32 v171, 16, v126
	v_lshlrev_b32_e32 v172, 16, v125
	v_lshlrev_b32_e32 v173, 16, v124
	v_lshlrev_b32_e32 v174, 16, v123
	v_lshlrev_b32_e32 v175, 16, v122
	v_lshlrev_b32_e32 v176, 16, v121
	v_lshlrev_b32_e32 v177, 16, v120
	v_lshlrev_b32_e32 v178, 16, v119
	v_lshlrev_b32_e32 v179, 16, v116
	v_lshlrev_b32_e32 v180, 16, v115
	v_lshlrev_b32_e32 v181, 16, v114
	v_lshlrev_b32_e32 v182, 16, v113
	s_cmp_gt_i32 s0, -15
	v_fma_f32 v185, v137, v81, v111
	v_lshlrev_b32_e32 v113, 16, v118
	s_cselect_b64 vcc, -1, 0
	s_cmp_gt_i32 s0, -16
	v_fmac_f32_e32 v185, v136, v108
	v_fma_f32 v127, v136, v81, v111
	v_cndmask_b32_e32 v183, 0, v113, vcc
	v_lshlrev_b32_e32 v113, 16, v117
	s_cselect_b64 vcc, -1, 0
	v_fmac_f32_e32 v185, v135, v109
	v_fmac_f32_e32 v127, v135, v108
	v_fma_f32 v126, v135, v81, v111
	v_cndmask_b32_e32 v184, 0, v113, vcc
	v_fmac_f32_e32 v185, v134, v110
	v_cvt_pk_bf16_f32 v113, v185, v129
	v_fmac_f32_e32 v127, v134, v109
	v_fmac_f32_e32 v126, v134, v108
	v_fma_f32 v125, v134, v81, v111
	ds_write_b16 v69, v113
	v_fmac_f32_e32 v127, v170, v110
	v_cvt_pk_bf16_f32 v113, v127, v129
	v_fmac_f32_e32 v126, v170, v109
	v_fmac_f32_e32 v125, v170, v108
	v_fma_f32 v124, v170, v81, v111
	ds_write_b16 v69, v113 offset:144
	v_fmac_f32_e32 v126, v171, v110
	v_cvt_pk_bf16_f32 v113, v126, v129
	v_fmac_f32_e32 v125, v171, v109
	v_fmac_f32_e32 v124, v171, v108
	v_fma_f32 v123, v171, v81, v111
	ds_write_b16 v69, v113 offset:288
	v_fmac_f32_e32 v125, v172, v110
	v_cvt_pk_bf16_f32 v113, v125, v129
	v_fmac_f32_e32 v124, v172, v109
	v_fmac_f32_e32 v123, v172, v108
	v_fma_f32 v122, v172, v81, v111
	ds_write_b16 v69, v113 offset:432
	v_fmac_f32_e32 v124, v173, v110
	v_cvt_pk_bf16_f32 v113, v124, v129
	v_fmac_f32_e32 v123, v173, v109
	v_fmac_f32_e32 v122, v173, v108
	v_fma_f32 v121, v173, v81, v111
	ds_write_b16 v69, v113 offset:576
	v_fmac_f32_e32 v123, v174, v110
	v_cvt_pk_bf16_f32 v113, v123, v129
	v_fmac_f32_e32 v122, v174, v109
	v_fmac_f32_e32 v121, v174, v108
	v_fma_f32 v120, v174, v81, v111
	ds_write_b16 v69, v113 offset:720
	v_fmac_f32_e32 v122, v175, v110
	v_cvt_pk_bf16_f32 v113, v122, v129
	v_fmac_f32_e32 v121, v175, v109
	v_fmac_f32_e32 v120, v175, v108
	v_fma_f32 v119, v175, v81, v111
	ds_write_b16 v69, v113 offset:864
	v_fmac_f32_e32 v121, v176, v110
	v_cvt_pk_bf16_f32 v113, v121, v129
	v_fmac_f32_e32 v120, v176, v109
	v_fmac_f32_e32 v119, v176, v108
	v_fma_f32 v118, v176, v81, v111
	ds_write_b16 v69, v113 offset:1008
	v_fmac_f32_e32 v120, v177, v110
	v_cvt_pk_bf16_f32 v113, v120, v129
	v_fmac_f32_e32 v119, v177, v109
	v_fmac_f32_e32 v118, v177, v108
	v_fma_f32 v117, v177, v81, v111
	ds_write_b16 v69, v113 offset:1152
	v_fmac_f32_e32 v119, v178, v110
	v_cvt_pk_bf16_f32 v113, v119, v129
	v_fmac_f32_e32 v118, v178, v109
	v_fmac_f32_e32 v117, v178, v108
	v_fma_f32 v116, v178, v81, v111
	ds_write_b16 v69, v113 offset:1296
	v_fmac_f32_e32 v118, v179, v110
	v_cvt_pk_bf16_f32 v113, v118, v129
	v_fmac_f32_e32 v117, v179, v109
	v_fmac_f32_e32 v116, v179, v108
	v_fma_f32 v115, v179, v81, v111
	ds_write_b16 v69, v113 offset:1440
	v_fmac_f32_e32 v117, v180, v110
	v_cvt_pk_bf16_f32 v113, v117, v129
	v_fmac_f32_e32 v116, v180, v109
	v_fmac_f32_e32 v115, v180, v108
	v_fma_f32 v114, v180, v81, v111
	ds_write_b16 v69, v113 offset:1584
	v_fmac_f32_e32 v116, v181, v110
	v_cvt_pk_bf16_f32 v113, v116, v129
	v_fmac_f32_e32 v115, v181, v109
	v_fmac_f32_e32 v114, v181, v108
	ds_write_b16 v69, v113 offset:1728
	v_fmac_f32_e32 v115, v182, v110
	v_cvt_pk_bf16_f32 v113, v115, v129
	v_fmac_f32_e32 v114, v182, v109
	ds_write_b16 v69, v113 offset:1872
	v_fmac_f32_e32 v114, v183, v110
	v_cvt_pk_bf16_f32 v113, v114, v129
	ds_write_b16 v69, v113 offset:2016
	v_fma_f32 v113, v181, v81, v111
	v_fmac_f32_e32 v113, v182, v108
	v_fmac_f32_e32 v113, v183, v109
	v_fmac_f32_e32 v113, v184, v110
	v_cvt_pk_bf16_f32 v134, v113, v129
	ds_write_b16 v69, v134 offset:2160
	s_waitcnt lgkmcnt(0)
	ds_read_b128 v[134:137], v106
	ds_read_b128 v[170:173], v106 offset:64
	s_waitcnt lgkmcnt(1)
	v_mfma_f32_16x16x32_bf16 v[174:177], v[134:137], v[0:3], 0
	v_add_u32_e32 v182, 0x800, v107
	v_add_u32_e32 v183, 0xc00, v107
	v_mfma_f32_16x16x32_bf16 v[178:181], v[134:137], v[8:11], 0
	s_waitcnt lgkmcnt(0)
	v_mfma_f32_16x16x32_bf16 v[174:177], v[170:173], v[4:7], v[174:177]
	v_mfma_f32_16x16x32_bf16 v[178:181], v[170:173], v[12:15], v[178:181]
	s_nop 7
	ds_write2_b32 v182, v174, v178 offset0:64 offset1:80
	ds_write2_b32 v182, v175, v179 offset0:132 offset1:148
	ds_write2_b32 v182, v176, v180 offset0:200 offset1:216
	ds_write2_b32 v183, v177, v181 offset0:12 offset1:28
	v_mfma_f32_16x16x32_bf16 v[174:177], v[134:137], v[16:19], 0
	v_mfma_f32_16x16x32_bf16 v[178:181], v[134:137], v[24:27], 0
	v_mfma_f32_16x16x32_bf16 v[174:177], v[170:173], v[20:23], v[174:177]
	v_mfma_f32_16x16x32_bf16 v[178:181], v[170:173], v[28:31], v[178:181]
	s_nop 7
	ds_write2_b32 v182, v174, v178 offset0:96 offset1:112
	ds_write2_b32 v182, v175, v179 offset0:164 offset1:180
	ds_write2_b32 v182, v176, v180 offset0:232 offset1:248
	ds_write2_b32 v183, v177, v181 offset0:44 offset1:60
	v_mfma_f32_16x16x32_bf16 v[174:177], v[134:137], v[32:35], 0
	v_add_u32_e32 v182, 0x1800, v107
	v_mfma_f32_16x16x32_bf16 v[178:181], v[134:137], v[40:43], 0
	v_mfma_f32_16x16x32_bf16 v[174:177], v[170:173], v[36:39], v[174:177]
	v_mfma_f32_16x16x32_bf16 v[178:181], v[170:173], v[44:47], v[178:181]
	s_nop 7
	ds_write2_b32 v182, v174, v178 offset0:128 offset1:144
	ds_write2_b32 v182, v175, v179 offset0:196 offset1:212
	v_add_u32_e32 v178, 0x1c00, v107
	ds_write2_b32 v178, v176, v180 offset0:8 offset1:24
	ds_write2_b32 v178, v177, v181 offset0:76 offset1:92
	v_mfma_f32_16x16x32_bf16 v[174:177], v[134:137], v[48:51], 0
	v_mfma_f32_16x16x32_bf16 v[134:137], v[134:137], v[56:59], 0
	v_mfma_f32_16x16x32_bf16 v[174:177], v[170:173], v[52:55], v[174:177]
	v_mfma_f32_16x16x32_bf16 v[134:137], v[170:173], v[60:63], v[134:137]
	s_nop 7
	ds_write2_b32 v182, v174, v134 offset0:160 offset1:176
	ds_write2_b32 v182, v175, v135 offset0:228 offset1:244
	ds_write2_b32 v178, v176, v136 offset0:40 offset1:56
	ds_write2_b32 v178, v177, v137 offset0:108 offset1:124
	s_waitcnt lgkmcnt(0)
	v_add_u32_e32 v134, 0x800, v70
	ds_read2_b32 v[134:135], v134 offset0:64 offset1:132
	v_add_u32_e32 v136, 0x1800, v70
	ds_read2_b32 v[136:137], v136 offset0:128 offset1:196
	s_waitcnt lgkmcnt(1)
	v_fmamk_f32 v134, v134, 0xbfb8aa3b, v112
	v_exp_f32_e32 v134, v134
	v_fmamk_f32 v135, v135, 0xbfb8aa3b, v112
	v_exp_f32_e32 v135, v135
	s_waitcnt lgkmcnt(0)
	v_fmamk_f32 v136, v136, 0xbfb8aa3b, v65
	v_add_f32_e32 v134, 1.0, v134
	v_rcp_f32_e32 v134, v134
	v_add_f32_e32 v135, 1.0, v135
	v_exp_f32_e32 v136, v136
	v_rcp_f32_e32 v135, v135
	v_mul_f32_e32 v134, v64, v134
	v_exp_f32_e32 v134, v134
	v_add_f32_e32 v136, 1.0, v136
	v_mul_f32_e32 v135, v64, v135
	v_rcp_f32_e32 v136, v136
	v_fma_f32 v170, -v134, v134, 1.0
	v_max_f32_e32 v170, 0, v170
	v_exp_f32_e32 v135, v135
	s_nop 0
	v_sqrt_f32_e32 v170, v170
	s_nop 0
	v_fmamk_f32 v137, v137, 0xbfb8aa3b, v65
	v_exp_f32_e32 v137, v137
	s_nop 0
	v_add_f32_e32 v137, 1.0, v137
	v_rcp_f32_e32 v137, v137
	s_nop 0
	v_mul_f32_e32 v136, v136, v170
	v_fma_f32 v170, -v135, v135, 1.0
	v_max_f32_e32 v170, 0, v170
	v_mul_f32_e32 v136, v185, v136
	v_sqrt_f32_e32 v170, v170
	s_nop 0
	v_fmac_f32_e32 v136, 0, v134
	v_mul_f32_e32 v137, v137, v170
	v_mul_f32_e32 v127, v127, v137
	v_mul_f32_e32 v170, v134, v135
	v_add_u32_e32 v134, 0xa00, v70
	v_fmac_f32_e32 v127, v135, v136
	ds_read2_b32 v[134:135], v134 offset0:72 offset1:140
	v_add_u32_e32 v171, 0x1c00, v70
	ds_read2_b32 v[136:137], v171 offset0:8 offset1:76
	s_waitcnt lgkmcnt(1)
	v_fmamk_f32 v134, v134, 0xbfb8aa3b, v112
	v_exp_f32_e32 v134, v134
	s_waitcnt lgkmcnt(0)
	v_fmamk_f32 v136, v136, 0xbfb8aa3b, v65
	v_exp_f32_e32 v136, v136
	v_add_f32_e32 v134, 1.0, v134
	v_rcp_f32_e32 v134, v134
	v_add_f32_e32 v136, 1.0, v136
	v_rcp_f32_e32 v136, v136
	v_mul_f32_e32 v134, v64, v134
	v_exp_f32_e32 v134, v134
	s_nop 0
	v_fma_f32 v172, -v134, v134, 1.0
	v_max_f32_e32 v172, 0, v172
	v_sqrt_f32_e32 v172, v172
	s_nop 0
	v_mul_f32_e32 v136, v136, v172
	v_mul_f32_e32 v126, v126, v136
	v_fmac_f32_e32 v126, v134, v127
	v_mul_f32_e32 v127, v170, v134
	v_fmamk_f32 v134, v135, 0xbfb8aa3b, v112
	v_exp_f32_e32 v134, v134
	v_fmamk_f32 v135, v137, 0xbfb8aa3b, v65
	v_exp_f32_e32 v135, v135
	v_add_f32_e32 v134, 1.0, v134
	v_rcp_f32_e32 v134, v134
	v_add_f32_e32 v135, 1.0, v135
	v_rcp_f32_e32 v135, v135
	v_mul_f32_e32 v134, v64, v134
	v_exp_f32_e32 v134, v134
	s_nop 0
	v_fma_f32 v136, -v134, v134, 1.0
	v_max_f32_e32 v136, 0, v136
	v_sqrt_f32_e32 v136, v136
	s_nop 0
	v_mul_f32_e32 v135, v135, v136
	v_mul_f32_e32 v125, v125, v135
	v_fmac_f32_e32 v125, v134, v126
	v_add_u32_e32 v126, 0xc00, v70
	v_mul_f32_e32 v136, v127, v134
	ds_read2_b32 v[126:127], v126 offset0:80 offset1:148
	ds_read2_b32 v[134:135], v171 offset0:144 offset1:212
	s_waitcnt lgkmcnt(1)
	v_fmamk_f32 v126, v126, 0xbfb8aa3b, v112
	v_exp_f32_e32 v126, v126
	s_waitcnt lgkmcnt(0)
	v_fmamk_f32 v134, v134, 0xbfb8aa3b, v65
	v_exp_f32_e32 v134, v134
	v_add_f32_e32 v126, 1.0, v126
	v_rcp_f32_e32 v126, v126
	v_add_f32_e32 v134, 1.0, v134
	v_rcp_f32_e32 v134, v134
	v_mul_f32_e32 v126, v64, v126
	v_exp_f32_e32 v126, v126
	s_nop 0
	v_fma_f32 v137, -v126, v126, 1.0
	v_max_f32_e32 v137, 0, v137
	v_sqrt_f32_e32 v137, v137
	s_nop 0
	v_mul_f32_e32 v134, v134, v137
	v_mul_f32_e32 v124, v124, v134
	v_fmac_f32_e32 v124, v126, v125
	v_mul_f32_e32 v125, v136, v126
	v_fmamk_f32 v126, v127, 0xbfb8aa3b, v112
	v_exp_f32_e32 v126, v126
	v_fmamk_f32 v127, v135, 0xbfb8aa3b, v65
	v_exp_f32_e32 v127, v127
	v_add_f32_e32 v126, 1.0, v126
	v_rcp_f32_e32 v126, v126
	v_add_f32_e32 v127, 1.0, v127
	v_rcp_f32_e32 v127, v127
	v_mul_f32_e32 v126, v64, v126
	v_exp_f32_e32 v126, v126
	s_nop 0
	v_fma_f32 v134, -v126, v126, 1.0
	v_max_f32_e32 v134, 0, v134
	v_sqrt_f32_e32 v134, v134
	s_nop 0
	v_mul_f32_e32 v127, v127, v134
	v_mul_f32_e32 v123, v123, v127
	v_fmac_f32_e32 v123, v126, v124
	v_add_u32_e32 v124, 0xe00, v70
	v_mul_f32_e32 v134, v125, v126
	ds_read2_b32 v[124:125], v124 offset0:88 offset1:156
	v_add_u32_e32 v135, 0x2000, v70
	ds_read2_b32 v[126:127], v135 offset0:24 offset1:92
	s_waitcnt lgkmcnt(1)
	v_fmamk_f32 v124, v124, 0xbfb8aa3b, v112
	v_exp_f32_e32 v124, v124
	s_waitcnt lgkmcnt(0)
	v_fmamk_f32 v126, v126, 0xbfb8aa3b, v65
	v_exp_f32_e32 v126, v126
	v_add_f32_e32 v124, 1.0, v124
	v_rcp_f32_e32 v124, v124
	v_add_f32_e32 v126, 1.0, v126
	v_rcp_f32_e32 v126, v126
	v_mul_f32_e32 v124, v64, v124
	v_exp_f32_e32 v124, v124
	s_nop 0
	v_fma_f32 v136, -v124, v124, 1.0
	v_max_f32_e32 v136, 0, v136
	v_sqrt_f32_e32 v136, v136
	s_nop 0
	v_mul_f32_e32 v126, v126, v136
	v_mul_f32_e32 v122, v122, v126
	v_fmac_f32_e32 v122, v124, v123
	v_mul_f32_e32 v123, v134, v124
	v_fmamk_f32 v124, v125, 0xbfb8aa3b, v112
	v_exp_f32_e32 v124, v124
	v_fmamk_f32 v125, v127, 0xbfb8aa3b, v65
	v_exp_f32_e32 v125, v125
	v_add_f32_e32 v124, 1.0, v124
	v_rcp_f32_e32 v124, v124
	v_add_f32_e32 v125, 1.0, v125
	v_rcp_f32_e32 v125, v125
	v_mul_f32_e32 v124, v64, v124
	v_exp_f32_e32 v124, v124
	s_nop 0
	v_fma_f32 v126, -v124, v124, 1.0
	v_max_f32_e32 v126, 0, v126
	v_sqrt_f32_e32 v126, v126
	s_nop 0
	v_mul_f32_e32 v125, v125, v126
	v_mul_f32_e32 v121, v121, v125
	v_fmac_f32_e32 v121, v124, v122
	v_add_u32_e32 v122, 0x1000, v70
	v_mul_f32_e32 v126, v123, v124
	ds_read2_b32 v[122:123], v122 offset0:96 offset1:164
	ds_read2_b32 v[124:125], v135 offset0:160 offset1:228
	s_waitcnt lgkmcnt(1)
	v_fmamk_f32 v122, v122, 0xbfb8aa3b, v112
	v_exp_f32_e32 v122, v122
	s_waitcnt lgkmcnt(0)
	v_fmamk_f32 v124, v124, 0xbfb8aa3b, v65
	v_exp_f32_e32 v124, v124
	v_add_f32_e32 v122, 1.0, v122
	v_rcp_f32_e32 v122, v122
	v_add_f32_e32 v124, 1.0, v124
	v_rcp_f32_e32 v124, v124
	v_mul_f32_e32 v122, v64, v122
	v_exp_f32_e32 v122, v122
	s_nop 0
	v_fma_f32 v127, -v122, v122, 1.0
	v_max_f32_e32 v127, 0, v127
	v_sqrt_f32_e32 v127, v127
	s_nop 0
	v_mul_f32_e32 v124, v124, v127
	v_mul_f32_e32 v120, v120, v124
	v_fmac_f32_e32 v120, v122, v121
	v_mul_f32_e32 v121, v126, v122
	v_fmamk_f32 v122, v123, 0xbfb8aa3b, v112
	v_exp_f32_e32 v122, v122
	v_fmamk_f32 v123, v125, 0xbfb8aa3b, v65
	v_exp_f32_e32 v123, v123
	v_add_f32_e32 v122, 1.0, v122
	v_rcp_f32_e32 v122, v122
	v_add_f32_e32 v123, 1.0, v123
	v_rcp_f32_e32 v123, v123
	v_mul_f32_e32 v122, v64, v122
	v_exp_f32_e32 v122, v122
	s_nop 0
	v_fma_f32 v124, -v122, v122, 1.0
	v_max_f32_e32 v124, 0, v124
	v_sqrt_f32_e32 v124, v124
	s_nop 0
	v_mul_f32_e32 v123, v123, v124
	v_mul_f32_e32 v119, v119, v123
	v_fmac_f32_e32 v119, v122, v120
	v_add_u32_e32 v120, 0x1200, v70
	v_mul_f32_e32 v124, v121, v122
	ds_read2_b32 v[120:121], v120 offset0:104 offset1:172
	v_add_u32_e32 v125, 0x2400, v70
	ds_read2_b32 v[122:123], v125 offset0:40 offset1:108
	s_waitcnt lgkmcnt(1)
	v_fmamk_f32 v120, v120, 0xbfb8aa3b, v112
	v_exp_f32_e32 v120, v120
	s_waitcnt lgkmcnt(0)
	v_fmamk_f32 v122, v122, 0xbfb8aa3b, v65
	v_exp_f32_e32 v122, v122
	v_add_f32_e32 v120, 1.0, v120
	v_rcp_f32_e32 v120, v120
	v_add_f32_e32 v122, 1.0, v122
	v_rcp_f32_e32 v122, v122
	v_mul_f32_e32 v120, v64, v120
	v_exp_f32_e32 v120, v120
	s_nop 0
	v_fma_f32 v126, -v120, v120, 1.0
	v_max_f32_e32 v126, 0, v126
	v_sqrt_f32_e32 v126, v126
	s_nop 0
	v_mul_f32_e32 v122, v122, v126
	v_mul_f32_e32 v118, v118, v122
	v_fmac_f32_e32 v118, v120, v119
	v_mul_f32_e32 v119, v124, v120
	v_fmamk_f32 v120, v121, 0xbfb8aa3b, v112
	v_exp_f32_e32 v120, v120
	v_fmamk_f32 v121, v123, 0xbfb8aa3b, v65
	v_exp_f32_e32 v121, v121
	v_add_f32_e32 v120, 1.0, v120
	v_rcp_f32_e32 v120, v120
	v_add_f32_e32 v121, 1.0, v121
	v_rcp_f32_e32 v121, v121
	v_mul_f32_e32 v120, v64, v120
	v_exp_f32_e32 v120, v120
	s_nop 0
	v_fma_f32 v122, -v120, v120, 1.0
	v_max_f32_e32 v122, 0, v122
	v_sqrt_f32_e32 v122, v122
	s_nop 0
	v_mul_f32_e32 v121, v121, v122
	v_mul_f32_e32 v117, v117, v121
	v_fmac_f32_e32 v117, v120, v118
	v_add_u32_e32 v118, 0x1400, v70
	v_mul_f32_e32 v122, v119, v120
	ds_read2_b32 v[118:119], v118 offset0:112 offset1:180
	ds_read2_b32 v[120:121], v125 offset0:176 offset1:244
	s_waitcnt lgkmcnt(1)
	v_fmamk_f32 v118, v118, 0xbfb8aa3b, v112
	v_exp_f32_e32 v118, v118
	s_waitcnt lgkmcnt(0)
	v_fmamk_f32 v120, v120, 0xbfb8aa3b, v65
	v_exp_f32_e32 v120, v120
	v_add_f32_e32 v118, 1.0, v118
	v_rcp_f32_e32 v118, v118
	v_add_f32_e32 v120, 1.0, v120
	v_rcp_f32_e32 v120, v120
	v_mul_f32_e32 v118, v64, v118
	v_exp_f32_e32 v118, v118
	s_nop 0
	v_fma_f32 v123, -v118, v118, 1.0
	v_max_f32_e32 v123, 0, v123
	v_sqrt_f32_e32 v123, v123
	s_nop 0
	v_mul_f32_e32 v120, v120, v123
	v_mul_f32_e32 v116, v116, v120
	v_fmac_f32_e32 v116, v118, v117
	v_mul_f32_e32 v117, v122, v118
	v_fmamk_f32 v118, v119, 0xbfb8aa3b, v112
	v_exp_f32_e32 v118, v118
	v_fmamk_f32 v119, v121, 0xbfb8aa3b, v65
	v_exp_f32_e32 v119, v119
	v_add_f32_e32 v118, 1.0, v118
	v_rcp_f32_e32 v118, v118
	v_add_f32_e32 v119, 1.0, v119
	v_rcp_f32_e32 v119, v119
	v_mul_f32_e32 v118, v64, v118
	v_exp_f32_e32 v118, v118
	s_nop 0
	v_fma_f32 v120, -v118, v118, 1.0
	v_max_f32_e32 v120, 0, v120
	v_sqrt_f32_e32 v120, v120
	s_nop 0
	v_mul_f32_e32 v119, v119, v120
	v_mul_f32_e32 v115, v115, v119
	v_fmac_f32_e32 v115, v118, v116
	v_add_u32_e32 v116, 0x1600, v70
	v_mul_f32_e32 v120, v117, v118
	ds_read2_b32 v[116:117], v116 offset0:120 offset1:188
	v_add_u32_e32 v118, 0x2800, v70
	ds_read2_b32 v[118:119], v118 offset0:56 offset1:124
	s_waitcnt lgkmcnt(1)
	v_fmamk_f32 v116, v116, 0xbfb8aa3b, v112
	v_exp_f32_e32 v116, v116
	s_waitcnt lgkmcnt(0)
	v_fmamk_f32 v118, v118, 0xbfb8aa3b, v65
	v_exp_f32_e32 v118, v118
	v_add_f32_e32 v116, 1.0, v116
	v_rcp_f32_e32 v116, v116
	v_add_f32_e32 v118, 1.0, v118
	v_rcp_f32_e32 v118, v118
	v_mul_f32_e32 v116, v64, v116
	v_exp_f32_e32 v116, v116
	s_nop 0
	v_fma_f32 v121, -v116, v116, 1.0
	v_max_f32_e32 v121, 0, v121
	v_sqrt_f32_e32 v121, v121
	s_nop 0
	v_mul_f32_e32 v118, v118, v121
	v_mul_f32_e32 v114, v114, v118
	v_fmac_f32_e32 v114, v116, v115
	v_mul_f32_e32 v115, v120, v116
	v_fmamk_f32 v116, v117, 0xbfb8aa3b, v112
	v_exp_f32_e32 v116, v116
	v_fmamk_f32 v117, v119, 0xbfb8aa3b, v65
	v_exp_f32_e32 v117, v117
	v_add_f32_e32 v116, 1.0, v116
	v_rcp_f32_e32 v116, v116
	v_add_f32_e32 v117, 1.0, v117
	v_rcp_f32_e32 v117, v117
	v_mul_f32_e32 v116, v64, v116
	v_exp_f32_e32 v116, v116
	s_nop 0
	v_fma_f32 v118, -v116, v116, 1.0
	v_max_f32_e32 v118, 0, v118
	v_sqrt_f32_e32 v118, v118
	s_nop 0
	v_mul_f32_e32 v117, v117, v118
	v_mul_f32_e32 v113, v113, v117
	v_fmac_f32_e32 v113, v116, v114
	v_mul_f32_e32 v114, v115, v116
	v_add_u32_e32 v115, s14, v67
	v_readlane_b32 s22, v242, 62
	s_and_b32 s22, s22, 3
	s_cmp_lg_u32 s22, 3
	s_cbranch_scc1 .Lcvf_b_done
	s_cmp_lt_i32 s41, 0
	s_cbranch_scc1 .Lcvf_b_done
	s_waitcnt vmcnt(0)
	s_cmp_eq_u64 s[44:45], 0
	s_cbranch_scc1 .Lcvf_nogain
	v_mul_f32_e32 v186, v186, v218
	v_mul_f32_e32 v187, v187, v218
	v_mul_f32_e32 v188, v188, v218
	v_mul_f32_e32 v189, v189, v218
	v_mul_f32_e32 v190, v190, v219
	v_mul_f32_e32 v191, v191, v219
	v_mul_f32_e32 v192, v192, v219
	v_mul_f32_e32 v193, v193, v219
	v_mul_f32_e32 v194, v194, v220
	v_mul_f32_e32 v195, v195, v220
	v_mul_f32_e32 v196, v196, v220
	v_mul_f32_e32 v197, v197, v220
	v_mul_f32_e32 v198, v198, v221
	v_mul_f32_e32 v199, v199, v221
	v_mul_f32_e32 v200, v200, v221
	v_mul_f32_e32 v201, v201, v221
	v_mul_f32_e32 v202, v202, v222
	v_mul_f32_e32 v203, v203, v222
	v_mul_f32_e32 v204, v204, v222
	v_mul_f32_e32 v205, v205, v222
	v_mul_f32_e32 v206, v206, v223
	v_mul_f32_e32 v207, v207, v223
	v_mul_f32_e32 v208, v208, v223
	v_mul_f32_e32 v209, v209, v223
	v_mul_f32_e32 v210, v210, v224
	v_mul_f32_e32 v211, v211, v224
	v_mul_f32_e32 v212, v212, v224
	v_mul_f32_e32 v213, v213, v224
	v_mul_f32_e32 v214, v214, v225
	v_mul_f32_e32 v215, v215, v225
	v_mul_f32_e32 v216, v216, v225
	v_mul_f32_e32 v217, v217, v225
